# sample-unit top-k argmax rounds: xor 1/2/4/8 shuffle steps via v_mov_b32_dpp instead of ds_bpermute_b32 (128 of 192 LDS round trips per unit removed)
# speedup vs baseline: 1.0027x; 1.0027x over previous
.LBB0_2340:
	s_or_b64 exec, exec, s[8:9]
	v_add_f32_e32 v2, v2, v3
	v_cmp_gt_u32_e32 vcc, 33, v1
	s_nop 1
	v_cndmask_b32_e32 v8, v136, v2, vcc
	v_and_b32_e32 v2, 64, v166
	v_add_u32_e32 v7, 64, v2
	v_xor_b32_e32 v2, 1, v166
	v_cmp_lt_i32_e32 vcc, v2, v7
	s_nop 1
	v_cndmask_b32_e32 v2, v166, v2, vcc
	v_lshlrev_b32_e32 v2, 2, v2
	v_mov_b32_dpp v3, v8 quad_perm:[1,0,3,2] row_mask:0xf bank_mask:0xf
	v_mov_b32_dpp v4, v1 quad_perm:[1,0,3,2] row_mask:0xf bank_mask:0xf
	s_waitcnt lgkmcnt(1)
	v_cmp_lt_f32_e64 s[8:9], v8, v3
	v_cmp_nlt_f32_e32 vcc, v8, v3
	s_and_saveexec_b64 s[10:11], vcc
	s_cbranch_execz .LBB0_2342
	v_cmp_eq_f32_e32 vcc, v8, v3
	s_waitcnt lgkmcnt(0)
	v_cmp_lt_i32_e64 s[6:7], v4, v1
	s_and_b64 s[6:7], vcc, s[6:7]
	s_andn2_b64 s[8:9], s[8:9], exec
	s_and_b64 s[6:7], s[6:7], exec
	s_or_b64 s[8:9], s[8:9], s[6:7]

.LBB0_2344:
	s_or_b64 exec, exec, s[6:7]
	v_xor_b32_e32 v3, 2, v166
	v_cmp_lt_i32_e32 vcc, v3, v7
	s_nop 1
	v_cndmask_b32_e32 v3, v166, v3, vcc
	v_lshlrev_b32_e32 v3, 2, v3
	s_waitcnt lgkmcnt(0)
	v_mov_b32_dpp v4, v10 quad_perm:[2,3,0,1] row_mask:0xf bank_mask:0xf
	v_mov_b32_dpp v5, v9 quad_perm:[2,3,0,1] row_mask:0xf bank_mask:0xf
	s_waitcnt lgkmcnt(1)
	v_cmp_lt_f32_e64 s[8:9], v11, v4
	v_cmp_nlt_f32_e32 vcc, v11, v4
	s_and_saveexec_b64 s[10:11], vcc
	s_cbranch_execz .LBB0_2346
	v_cmp_eq_f32_e32 vcc, v11, v4
	s_waitcnt lgkmcnt(0)
	v_cmp_lt_i32_e64 s[6:7], v5, v9
	s_and_b64 s[6:7], vcc, s[6:7]
	s_andn2_b64 s[8:9], s[8:9], exec
	s_and_b64 s[6:7], s[6:7], exec
	s_or_b64 s[8:9], s[8:9], s[6:7]

.LBB0_2348:
	s_or_b64 exec, exec, s[6:7]
	v_xor_b32_e32 v4, 4, v166
	v_cmp_lt_i32_e32 vcc, v4, v7
	s_nop 1
	v_cndmask_b32_e32 v4, v166, v4, vcc
	v_lshlrev_b32_e32 v4, 2, v4
	s_waitcnt lgkmcnt(0)
	v_mov_b32_dpp v5, v10 row_half_mirror row_mask:0xf bank_mask:0xf
	v_mov_b32_dpp v6, v9 row_half_mirror row_mask:0xf bank_mask:0xf
	s_waitcnt lgkmcnt(1)
	v_cmp_lt_f32_e64 s[8:9], v11, v5
	v_cmp_nlt_f32_e32 vcc, v11, v5
	s_and_saveexec_b64 s[10:11], vcc
	s_cbranch_execz .LBB0_2350
	v_cmp_eq_f32_e32 vcc, v11, v5
	s_waitcnt lgkmcnt(0)
	v_cmp_lt_i32_e64 s[6:7], v6, v9
	s_and_b64 s[6:7], vcc, s[6:7]
	s_andn2_b64 s[8:9], s[8:9], exec
	s_and_b64 s[6:7], s[6:7], exec
	s_or_b64 s[8:9], s[8:9], s[6:7]

.LBB0_2352:
	s_or_b64 exec, exec, s[6:7]
	v_xor_b32_e32 v5, 8, v166
	v_cmp_lt_i32_e32 vcc, v5, v7
	s_nop 1
	v_cndmask_b32_e32 v5, v166, v5, vcc
	v_lshlrev_b32_e32 v5, 2, v5
	s_waitcnt lgkmcnt(0)
	v_mov_b32_dpp v6, v10 row_mirror row_mask:0xf bank_mask:0xf
	v_mov_b32_dpp v12, v9 row_mirror row_mask:0xf bank_mask:0xf
	s_waitcnt lgkmcnt(1)
	v_cmp_lt_f32_e64 s[8:9], v11, v6
	v_cmp_nlt_f32_e32 vcc, v11, v6
	s_and_saveexec_b64 s[10:11], vcc
	s_cbranch_execz .LBB0_2354
	v_cmp_eq_f32_e32 vcc, v11, v6
	s_waitcnt lgkmcnt(0)
	v_cmp_lt_i32_e64 s[6:7], v12, v9
	s_and_b64 s[6:7], vcc, s[6:7]
	s_andn2_b64 s[8:9], s[8:9], exec
	s_and_b64 s[6:7], s[6:7], exec
	s_or_b64 s[8:9], s[8:9], s[6:7]

.LBB0_2364:
	s_or_b64 exec, exec, s[6:7]
	v_cmp_ne_u32_e64 s[6:7], v9, v1
	v_mov_b32_dpp v13, v1 quad_perm:[1,0,3,2] row_mask:0xf bank_mask:0xf
	s_nop 0
	v_cndmask_b32_e64 v8, v137, v8, s[6:7]
	s_nop 1
	v_mov_b32_dpp v12, v8 quad_perm:[1,0,3,2] row_mask:0xf bank_mask:0xf
	s_waitcnt lgkmcnt(0)
	v_cmp_lt_f32_e64 s[10:11], v8, v12
	v_cmp_nlt_f32_e64 s[6:7], v8, v12
	s_and_saveexec_b64 s[12:13], s[6:7]
	v_cmp_eq_f32_e64 s[6:7], v8, v12
	v_cmp_lt_i32_e64 s[8:9], v13, v1
	s_and_b64 s[6:7], s[6:7], s[8:9]
	s_andn2_b64 s[8:9], s[10:11], exec
	s_and_b64 s[6:7], s[6:7], exec
	s_or_b64 s[10:11], s[8:9], s[6:7]
	s_or_b64 exec, exec, s[12:13]
	v_mov_b32_e32 v10, v8
	v_mov_b32_e32 v9, v1
	v_mov_b32_e32 v11, v8
	s_and_saveexec_b64 s[6:7], s[10:11]
	v_mov_b32_e32 v10, v12
	v_mov_b32_e32 v9, v13
	v_mov_b32_e32 v11, v12
	s_or_b64 exec, exec, s[6:7]
	v_mov_b32_dpp v12, v10 quad_perm:[2,3,0,1] row_mask:0xf bank_mask:0xf
	v_mov_b32_dpp v13, v9 quad_perm:[2,3,0,1] row_mask:0xf bank_mask:0xf
	s_waitcnt lgkmcnt(1)
	v_cmp_lt_f32_e64 s[10:11], v11, v12
	v_cmp_nlt_f32_e64 s[6:7], v11, v12
	s_and_saveexec_b64 s[12:13], s[6:7]
	s_cbranch_execz .LBB0_2370
	v_cmp_eq_f32_e64 s[6:7], v11, v12
	s_waitcnt lgkmcnt(0)
	v_cmp_lt_i32_e64 s[8:9], v13, v9
	s_and_b64 s[6:7], s[6:7], s[8:9]
	s_andn2_b64 s[8:9], s[10:11], exec
	s_and_b64 s[6:7], s[6:7], exec
	s_or_b64 s[10:11], s[8:9], s[6:7]

.LBB0_2372:
	s_or_b64 exec, exec, s[6:7]
	s_nop 1
	v_mov_b32_dpp v12, v10 row_half_mirror row_mask:0xf bank_mask:0xf
	s_waitcnt lgkmcnt(1)
	v_mov_b32_dpp v13, v9 row_half_mirror row_mask:0xf bank_mask:0xf
	s_waitcnt lgkmcnt(1)
	v_cmp_lt_f32_e64 s[10:11], v11, v12
	v_cmp_nlt_f32_e64 s[6:7], v11, v12
	s_and_saveexec_b64 s[12:13], s[6:7]
	s_cbranch_execz .LBB0_2374
	v_cmp_eq_f32_e64 s[6:7], v11, v12
	s_waitcnt lgkmcnt(0)
	v_cmp_lt_i32_e64 s[8:9], v13, v9
	s_and_b64 s[6:7], s[6:7], s[8:9]
	s_andn2_b64 s[8:9], s[10:11], exec
	s_and_b64 s[6:7], s[6:7], exec
	s_or_b64 s[10:11], s[8:9], s[6:7]

.LBB0_2376:
	s_or_b64 exec, exec, s[6:7]
	s_nop 1
	v_mov_b32_dpp v12, v10 row_mirror row_mask:0xf bank_mask:0xf
	s_waitcnt lgkmcnt(1)
	v_mov_b32_dpp v13, v9 row_mirror row_mask:0xf bank_mask:0xf
	s_waitcnt lgkmcnt(1)
	v_cmp_lt_f32_e64 s[10:11], v11, v12
	v_cmp_nlt_f32_e64 s[6:7], v11, v12
	s_and_saveexec_b64 s[12:13], s[6:7]
	s_cbranch_execz .LBB0_2378
	v_cmp_eq_f32_e64 s[6:7], v11, v12
	s_waitcnt lgkmcnt(0)
	v_cmp_lt_i32_e64 s[8:9], v13, v9
	s_and_b64 s[6:7], s[6:7], s[8:9]
	s_andn2_b64 s[8:9], s[10:11], exec
	s_and_b64 s[6:7], s[6:7], exec
	s_or_b64 s[10:11], s[8:9], s[6:7]

.LBB0_2700:
	s_or_b64 exec, exec, s[6:7]
	v_cmp_ne_u32_e64 s[6:7], v9, v1
	s_waitcnt lgkmcnt(0)
	v_mov_b32_dpp v10, v1 quad_perm:[1,0,3,2] row_mask:0xf bank_mask:0xf
	v_cndmask_b32_e64 v8, v137, v8, s[6:7]
	s_nop 1
	v_mov_b32_dpp v9, v8 quad_perm:[1,0,3,2] row_mask:0xf bank_mask:0xf
	s_waitcnt lgkmcnt(0)
	v_cmp_lt_f32_e64 s[10:11], v8, v9
	v_cmp_nlt_f32_e64 s[6:7], v8, v9
	s_and_saveexec_b64 s[12:13], s[6:7]
	v_cmp_eq_f32_e64 s[6:7], v8, v9
	v_cmp_lt_i32_e64 s[8:9], v10, v1
	s_and_b64 s[6:7], s[6:7], s[8:9]
	s_andn2_b64 s[8:9], s[10:11], exec
	s_and_b64 s[6:7], s[6:7], exec
	s_or_b64 s[10:11], s[8:9], s[6:7]
	s_or_b64 exec, exec, s[12:13]
	v_mov_b32_e32 v2, v1
	s_and_saveexec_b64 s[6:7], s[10:11]
	v_mov_b32_e32 v8, v9
	v_mov_b32_e32 v2, v10
	s_or_b64 exec, exec, s[6:7]
	v_mov_b32_dpp v9, v8 quad_perm:[2,3,0,1] row_mask:0xf bank_mask:0xf
	v_mov_b32_dpp v3, v2 quad_perm:[2,3,0,1] row_mask:0xf bank_mask:0xf
	s_waitcnt lgkmcnt(1)
	v_cmp_lt_f32_e64 s[10:11], v8, v9
	v_cmp_nlt_f32_e64 s[6:7], v8, v9
	s_and_saveexec_b64 s[12:13], s[6:7]
	s_cbranch_execz .LBB0_2706
	v_cmp_eq_f32_e64 s[6:7], v8, v9
	s_waitcnt lgkmcnt(0)
	v_cmp_lt_i32_e64 s[8:9], v3, v2
	s_and_b64 s[6:7], s[6:7], s[8:9]
	s_andn2_b64 s[8:9], s[10:11], exec
	s_and_b64 s[6:7], s[6:7], exec
	s_or_b64 s[10:11], s[8:9], s[6:7]

.LBB0_2708:
	s_or_b64 exec, exec, s[6:7]
	s_waitcnt lgkmcnt(0)
	v_mov_b32_dpp v3, v8 row_half_mirror row_mask:0xf bank_mask:0xf
	v_mov_b32_dpp v4, v2 row_half_mirror row_mask:0xf bank_mask:0xf
	s_waitcnt lgkmcnt(1)
	v_cmp_lt_f32_e64 s[10:11], v8, v3
	v_cmp_nlt_f32_e64 s[6:7], v8, v3
	s_and_saveexec_b64 s[12:13], s[6:7]
	s_cbranch_execz .LBB0_2710
	v_cmp_eq_f32_e64 s[6:7], v8, v3
	s_waitcnt lgkmcnt(0)
	v_cmp_lt_i32_e64 s[8:9], v4, v2
	s_and_b64 s[6:7], s[6:7], s[8:9]
	s_andn2_b64 s[8:9], s[10:11], exec
	s_and_b64 s[6:7], s[6:7], exec
	s_or_b64 s[10:11], s[8:9], s[6:7]

.LBB0_2712:
	s_or_b64 exec, exec, s[6:7]
	s_nop 1
	v_mov_b32_dpp v3, v8 row_mirror row_mask:0xf bank_mask:0xf
	s_waitcnt lgkmcnt(1)
	v_mov_b32_dpp v4, v2 row_mirror row_mask:0xf bank_mask:0xf
	s_waitcnt lgkmcnt(1)
	v_cmp_lt_f32_e64 s[10:11], v8, v3
	v_cmp_nlt_f32_e64 s[6:7], v8, v3
	s_and_saveexec_b64 s[12:13], s[6:7]
	s_cbranch_execz .LBB0_2714
	v_cmp_eq_f32_e64 s[6:7], v8, v3
	s_waitcnt lgkmcnt(0)
	v_cmp_lt_i32_e64 s[8:9], v4, v2
	s_and_b64 s[6:7], s[6:7], s[8:9]
	s_andn2_b64 s[8:9], s[10:11], exec
	s_and_b64 s[6:7], s[6:7], exec
	s_or_b64 s[10:11], s[8:9], s[6:7]
